# v85 + P1 epilogue else-branch wait counted (vmcnt(2) instead of vmcnt(0) right after the two TU-halo stores)
# baseline (speedup 1.0000x reference)
.LBB0_151:
	s_andn2_saveexec_b64 s[84:85], s[84:85]
	s_cbranch_execz .LBB0_153
	s_ashr_i32 s83, s82, 31
	s_lshl_b64 s[14:15], s[82:83], 13
	v_lshl_add_u64 v[4:5], v[158:159], 0, s[14:15]
	v_lshl_add_u64 v[4:5], v[4:5], 0, v[172:173]
	global_store_dwordx4 v[4:5], v[128:131], off
	v_lshl_add_u64 v[4:5], v[160:161], 0, s[14:15]
	v_lshl_add_u64 v[4:5], v[4:5], 0, v[172:173]
	global_store_dwordx4 v[4:5], v[132:135], off
	s_waitcnt vmcnt(2)
	v_mov_b32_e32 v4, v115
	v_mov_b32_e32 v8, v113
